# grid barrier: s_sleep removed from the poll loop (a longer sleep measured clearly slower, so detection latency matters)
# baseline (speedup 1.0000x reference)
; DI void fast_grid_barrier(unsigned* ctr, unsigned target) {
;     ...
;     if (threadIdx.x == 0) {
;         __builtin_amdgcn_fence(__ATOMIC_RELEASE, "agent");
;         asm volatile("s_waitcnt vmcnt(0)" ::: "memory");
;         __hip_atomic_fetch_add(ctr, 1u, __ATOMIC_RELAXED, __HIP_MEMORY_SCOPE_AGENT);
;         while (__hip_atomic_load(ctr, __ATOMIC_RELAXED, __HIP_MEMORY_SCOPE_AGENT) < target) __builtin_amdgcn_s_sleep(1);
;         __builtin_amdgcn_fence(__ATOMIC_ACQUIRE, "agent");
;         asm volatile("s_waitcnt vmcnt(0)" ::: "memory");
.LBB0_10:
	global_load_dword v0, v165, s[14:15] sc1
	s_waitcnt vmcnt(0)
	v_cmp_gt_u32_e32 vcc, s5, v0
	s_cbranch_vccnz .LBB0_10
